# RWKV step loop rewritten by hand: state held as row pairs so the dot products accumulate packed (no horizontal adds, no v_mov copies); f32 math as before
# speedup vs baseline: 1.0075x; 1.0050x over previous
; __device__ __forceinline__ unsigned pack2(float a, float b) { const f32x2n v = {a, b}; const bf16x2n h = __builtin_convertvector(v, bf16x2n); return __builtin_bit_cast(unsigned, h); }
; __device__ void mx_rwkv(const Params& P, int l, int item, char* lds) {
;     ...
;         for (int st = 0; st < 16; ++st) {
;             const int sp = d ? 15 - st : st;
;             const f32x4 a4 = *(const f32x4*)(VA + sp * 64 + j0), wr4 = *(const f32x4*)(VWR + sp * 64 + j0), w4 = *(const f32x4*)(VW + sp * 64 + j0);
;             const f32x4 b4 = *(const f32x4*)(VB + sp * 64 + j0), k4 = *(const f32x4*)(VK + sp * 64 + j0), v4 = *(const f32x4*)(VV + sp * 64 + s * 4);
;             const float br = SC[sp * 2], kr = SC[sp * 2 + 1];
;             float psa[4], py[4];
;             typedef float f32x2 __attribute__((ext_vector_type(2)));
;             const f32x2 a01 = {a4[0], a4[1]}, a23 = {a4[2], a4[3]}, r01 = {wr4[0], wr4[1]}, r23 = {wr4[2], wr4[3]};
; #pragma unroll
;             for (int i = 0; i < 4; ++i) {
;                 const f32x2 s01 = {S[i][0], S[i][1]}, s23 = {S[i][2], S[i][3]};
;                 f32x2 ta = s01 * a01; ta = s23 * a23 + ta;
;                 f32x2 ty = s01 * r01; ty = s23 * r23 + ty;
;                 psa[i] = ta.x + ta.y; py[i] = ty.x + ty.y;
;             }
;     ...
;             RS8("row_ror:8"); RS8("row_ror:4"); RS8("row_ror:2"); RS8("row_ror:1");
;             asm volatile("s_nop 1" ::: "memory");
;             float y[4];
; #pragma unroll
;             for (int i = 0; i < 4; ++i) {
;                 y[i] = py[i] + psa[i] * br + v4[i] * kr;
; #pragma unroll
;                 for (int j = 0; j < 4; ++j) S[i][j] = S[i][j] * w4[j] + (psa[i] * b4[j] + v4[i] * k4[j]);
;             }
;             if (jg == 0) *(u32x2*)(Yd + (size_t)(t0 + sp) * 512 + s * 4) = (u32x2){pack2(y[0], y[1]), pack2(y[2], y[3])};
;         }
.LBB0_252:
	s_or_b64 exec, exec, s[0:1]
	s_waitcnt lgkmcnt(0)
	v_pk_mul_f32 v[88:89], v[90:91], v[76:77] op_sel_hi:[1,0]
	v_pk_mul_f32 v[92:93], v[2:3], v[76:77] op_sel_hi:[1,0]
	v_pk_fma_f32 v[88:89], v[84:85], v[80:81], v[88:89] op_sel_hi:[1,0,1]
	v_pk_fma_f32 v[92:93], v[86:87], v[80:81], v[92:93] op_sel_hi:[1,0,1]
	v_pk_fma_f32 v[108:109], v[108:109], v[72:73], v[88:89] op_sel_hi:[1,0,1]
	v_pk_fma_f32 v[110:111], v[110:111], v[72:73], v[92:93] op_sel_hi:[1,0,1]
	s_add_i32 s29, s29, 1
	v_pk_mul_f32 v[88:89], v[90:91], v[76:77] op_sel:[0,1]
	v_pk_mul_f32 v[92:93], v[2:3], v[76:77] op_sel:[0,1]
	v_pk_fma_f32 v[88:89], v[84:85], v[80:81], v[88:89] op_sel:[0,1,0]
	v_pk_fma_f32 v[92:93], v[86:87], v[80:81], v[92:93] op_sel:[0,1,0]
	v_pk_fma_f32 v[112:113], v[112:113], v[72:73], v[88:89] op_sel:[0,1,0]
	v_pk_fma_f32 v[114:115], v[114:115], v[72:73], v[92:93] op_sel:[0,1,0]
	s_add_i32 s34, s34, -1
	v_pk_mul_f32 v[88:89], v[90:91], v[78:79] op_sel_hi:[1,0]
	v_pk_mul_f32 v[92:93], v[2:3], v[78:79] op_sel_hi:[1,0]
	v_pk_fma_f32 v[88:89], v[84:85], v[82:83], v[88:89] op_sel_hi:[1,0,1]
	v_pk_fma_f32 v[92:93], v[86:87], v[82:83], v[92:93] op_sel_hi:[1,0,1]
	v_pk_fma_f32 v[116:117], v[116:117], v[74:75], v[88:89] op_sel_hi:[1,0,1]
	v_pk_fma_f32 v[118:119], v[118:119], v[74:75], v[92:93] op_sel_hi:[1,0,1]
	v_pk_mul_f32 v[88:89], v[90:91], v[78:79] op_sel:[0,1]
	v_pk_mul_f32 v[92:93], v[2:3], v[78:79] op_sel:[0,1]
	v_pk_fma_f32 v[88:89], v[84:85], v[82:83], v[88:89] op_sel:[0,1,0]
	v_pk_fma_f32 v[92:93], v[86:87], v[82:83], v[92:93] op_sel:[0,1,0]
	v_pk_fma_f32 v[120:121], v[120:121], v[74:75], v[88:89] op_sel:[0,1,0]
	v_pk_fma_f32 v[122:123], v[122:123], v[74:75], v[92:93] op_sel:[0,1,0]
	s_cmp_eq_u32 s29, 16
	s_cbranch_scc1 .LBB0_198
.LBB0_253:
	s_and_b64 s[0:1], s[50:51], exec
	s_cselect_b32 s24, s29, s34
	s_lshl_b32 s0, s24, 8
	v_add_u32_e32 v0, s0, v134
	ds_read_b128 v[124:127], v0
	ds_read_b128 v[142:145], v0 offset:4096
	ds_read_b128 v[72:75], v0 offset:8192
	ds_read_b128 v[76:79], v0 offset:12288
	v_add_u32_e32 v2, s0, v98
	ds_read_b128 v[80:83], v0 offset:16384
	ds_read_b128 v[84:87], v2 offset:20480
	s_lshl_b32 s0, s24, 3
	v_mov_b32_e32 v0, s0
	ds_read_b64 v[92:93], v0 offset:28672
	s_waitcnt lgkmcnt(5)
	v_pk_mul_f32 v[90:91], v[108:109], v[124:125] op_sel_hi:[1,0]
	v_pk_mul_f32 v[2:3], v[110:111], v[124:125] op_sel_hi:[1,0]
	v_pk_mul_f32 v[94:95], v[108:109], v[142:143] op_sel_hi:[1,0]
	v_pk_mul_f32 v[96:97], v[110:111], v[142:143] op_sel_hi:[1,0]
	s_nop 0
	v_pk_fma_f32 v[90:91], v[112:113], v[124:125], v[90:91] op_sel:[0,1,0]
	v_pk_fma_f32 v[2:3], v[114:115], v[124:125], v[2:3] op_sel:[0,1,0]
	v_pk_fma_f32 v[94:95], v[112:113], v[142:143], v[94:95] op_sel:[0,1,0]
	v_pk_fma_f32 v[96:97], v[114:115], v[142:143], v[96:97] op_sel:[0,1,0]
	v_pk_fma_f32 v[90:91], v[116:117], v[126:127], v[90:91] op_sel_hi:[1,0,1]
	v_pk_fma_f32 v[2:3], v[118:119], v[126:127], v[2:3] op_sel_hi:[1,0,1]
	v_pk_fma_f32 v[94:95], v[116:117], v[144:145], v[94:95] op_sel_hi:[1,0,1]
	v_pk_fma_f32 v[96:97], v[118:119], v[144:145], v[96:97] op_sel_hi:[1,0,1]
	v_pk_fma_f32 v[90:91], v[120:121], v[126:127], v[90:91] op_sel:[0,1,0]
	v_pk_fma_f32 v[2:3], v[122:123], v[126:127], v[2:3] op_sel:[0,1,0]
	v_pk_fma_f32 v[94:95], v[120:121], v[144:145], v[94:95] op_sel:[0,1,0]
	v_pk_fma_f32 v[96:97], v[122:123], v[144:145], v[96:97] op_sel:[0,1,0]
	s_nop 0
	v_add_f32_dpp v90, v90, v90 row_ror:8 row_mask:0xf bank_mask:0xf
	v_add_f32_dpp v91, v91, v91 row_ror:8 row_mask:0xf bank_mask:0xf
	v_add_f32_dpp v2, v2, v2 row_ror:8 row_mask:0xf bank_mask:0xf
	v_add_f32_dpp v3, v3, v3 row_ror:8 row_mask:0xf bank_mask:0xf
	v_add_f32_dpp v94, v94, v94 row_ror:8 row_mask:0xf bank_mask:0xf
	v_add_f32_dpp v95, v95, v95 row_ror:8 row_mask:0xf bank_mask:0xf
	v_add_f32_dpp v96, v96, v96 row_ror:8 row_mask:0xf bank_mask:0xf
	v_add_f32_dpp v97, v97, v97 row_ror:8 row_mask:0xf bank_mask:0xf
	v_add_f32_dpp v90, v90, v90 row_ror:4 row_mask:0xf bank_mask:0xf
	v_add_f32_dpp v91, v91, v91 row_ror:4 row_mask:0xf bank_mask:0xf
	v_add_f32_dpp v2, v2, v2 row_ror:4 row_mask:0xf bank_mask:0xf
	v_add_f32_dpp v3, v3, v3 row_ror:4 row_mask:0xf bank_mask:0xf
	v_add_f32_dpp v94, v94, v94 row_ror:4 row_mask:0xf bank_mask:0xf
	v_add_f32_dpp v95, v95, v95 row_ror:4 row_mask:0xf bank_mask:0xf
	v_add_f32_dpp v96, v96, v96 row_ror:4 row_mask:0xf bank_mask:0xf
	v_add_f32_dpp v97, v97, v97 row_ror:4 row_mask:0xf bank_mask:0xf
	v_add_f32_dpp v90, v90, v90 row_ror:2 row_mask:0xf bank_mask:0xf
	v_add_f32_dpp v91, v91, v91 row_ror:2 row_mask:0xf bank_mask:0xf
	v_add_f32_dpp v2, v2, v2 row_ror:2 row_mask:0xf bank_mask:0xf
	v_add_f32_dpp v3, v3, v3 row_ror:2 row_mask:0xf bank_mask:0xf
	v_add_f32_dpp v94, v94, v94 row_ror:2 row_mask:0xf bank_mask:0xf
	v_add_f32_dpp v95, v95, v95 row_ror:2 row_mask:0xf bank_mask:0xf
	v_add_f32_dpp v96, v96, v96 row_ror:2 row_mask:0xf bank_mask:0xf
	v_add_f32_dpp v97, v97, v97 row_ror:2 row_mask:0xf bank_mask:0xf
	v_add_f32_dpp v90, v90, v90 row_ror:1 row_mask:0xf bank_mask:0xf
	v_add_f32_dpp v91, v91, v91 row_ror:1 row_mask:0xf bank_mask:0xf
	v_add_f32_dpp v2, v2, v2 row_ror:1 row_mask:0xf bank_mask:0xf
	v_add_f32_dpp v3, v3, v3 row_ror:1 row_mask:0xf bank_mask:0xf
	v_add_f32_dpp v94, v94, v94 row_ror:1 row_mask:0xf bank_mask:0xf
	v_add_f32_dpp v95, v95, v95 row_ror:1 row_mask:0xf bank_mask:0xf
	v_add_f32_dpp v96, v96, v96 row_ror:1 row_mask:0xf bank_mask:0xf
	v_add_f32_dpp v97, v97, v97 row_ror:1 row_mask:0xf bank_mask:0xf
	s_and_saveexec_b64 s[0:1], s[44:45]
	s_cbranch_execz .LBB0_252
	s_waitcnt lgkmcnt(0)
	v_pk_fma_f32 v[96:97], v[92:93], v[2:3], v[96:97] op_sel_hi:[0,1,1]
	v_pk_fma_f32 v[94:95], v[92:93], v[90:91], v[94:95] op_sel_hi:[0,1,1]
	s_add_i32 s24, s24, s28
	v_pk_fma_f32 v[96:97], v[86:87], v[92:93], v[96:97] op_sel:[0,1,0]
	v_pk_fma_f32 v[92:93], v[84:85], v[92:93], v[94:95] op_sel:[0,1,0]
	s_lshl_b32 s24, s24, 10
	v_cvt_pk_bf16_f32 v92, v92, v93
	v_cvt_pk_bf16_f32 v93, v96, v97
	v_lshl_add_u64 v[94:95], v[100:101], 0, s[24:25]
	global_store_dwordx2 v[94:95], v[92:93], off
	s_branch .LBB0_252
